# p0c layer-0 operand pass: warm-up touches for each row's later chunks right after chunk 0's loads (serialised chunk loads then hit in cache)
# baseline (speedup 1.0000x reference)
; __device__ __forceinline__ unsigned pk2(float lo, float hi) { unsigned r; asm("v_cvt_pk_bf16_f32 %0, %1, %2" : "=v"(r) : "v"(lo), "v"(hi)); return r; }
; __device__ __forceinline__ void p0c(LAS unsigned char* lds, int G, const int wave_s) {
;     ...
;       for (int i = 0; i < nlat + nctx; ++i) { const bool isc = i >= nlat; const int row = isc ? ML + (int)blockIdx.x * 32 + wave * 4 + (i - nlat) : gw + i * NGW;
;           const int v = vec_of_row(row); const float* xr = isc ? Pp->in[2] + (size_t)(row - ML) * D : Pp->in[0] + (size_t)row * D; float s = 0.f;
; #pragma unroll
;           for (int j = 0; j < 4; ++j) { const int c = lane * 8 + 512 * j; const f32x4 a = __builtin_nontemporal_load((const f32x4*)(xr + c)), b = __builtin_nontemporal_load((const f32x4*)(xr + c + 4));
;               s += (a[0] * a[0] + a[1] * a[1]) + (a[2] * a[2] + a[3] * a[3]) + (b[0] * b[0] + b[1] * b[1]) + (b[2] * b[2] + b[3] * b[3]);
;               const f32x4 g0 = *(const f32x4*)(Pp->in[4] + c), g1 = *(const f32x4*)(Pp->in[4] + c + 4), m0 = *(const f32x4*)(MOD + (size_t)v * 6 * D + D + c), m1 = *(const f32x4*)(MOD + (size_t)v * 6 * D + D + c + 4);
;               const f32x4 ga = a * g0 * (m0 + 1.0f), gb = b * g1 * (m1 + 1.0f);
;               u32x4 w; w.x = pk2(ga[0], ga[1]); w.y = pk2(ga[2], ga[3]); w.z = pk2(gb[0], gb[1]); w.w = pk2(gb[2], gb[3]);
;               *(u32x4*)(AN + (size_t)row * D + c) = w; }
.LBB0_147:
	s_cmpk_lt_u32 s8, 0x2000
	s_cselect_b32 s50, s73, 0x6000
	s_cmpk_gt_i32 s8, 0xfff
	s_cselect_b32 s50, s50, 0
	s_lshl_b32 s50, s50, 2
	s_add_u32 s50, s18, s50
	s_addc_u32 s51, s19, 0
	v_lshlrev_b64 v[22:23], 2, v[80:81]
	v_lshl_add_u64 v[24:25], s[50:51], 0, v[22:23]
	v_lshl_add_u64 v[28:29], s[48:49], 0, v[22:23]
	v_add_co_u32_e32 v26, vcc, s73, v24
	s_mov_b64 s[48:49], 0x2000
	s_nop 0
	v_addc_co_u32_e32 v27, vcc, 0, v25, vcc
	v_lshl_add_u64 v[42:43], v[24:25], 0, s[48:49]
	global_load_dwordx4 v[0:3], v[28:29], off offset:16 nt
	global_load_dwordx4 v[4:7], v[28:29], off nt
	global_load_dwordx4 v[8:11], v[16:17], off offset:16
	global_load_dwordx4 v[12:15], v[16:17], off
	global_load_dwordx4 v[30:33], v[26:27], off offset:-4096
	global_load_dwordx4 v[34:37], v[42:43], off offset:16
	s_lshl_b64 s[48:49], s[8:9], 12
	v_lshl_add_u64 v[22:23], v[90:91], 0, s[48:49]
	s_movk_i32 s50, 0x1000
	v_add_co_u32_e32 v54, vcc, s50, v28
	s_mov_b64 s[48:49], 0x3000
	s_nop 0
	v_addc_co_u32_e32 v55, vcc, 0, v29, vcc
	global_load_dword v100, v[28:29], off offset:2048
	global_load_dword v101, v[54:55], off
	global_load_dword v102, v[54:55], off offset:2048
	v_lshl_add_u64 v[46:47], v[28:29], 0, s[28:29]
	v_lshl_add_u64 v[50:51], v[24:25], 0, s[48:49]
	s_mov_b64 s[50:51], 0x3800
	v_lshl_add_u64 v[24:25], v[24:25], 0, s[50:51]
	v_xor_b32_e32 v58, 1, v157
	v_xor_b32_e32 v59, 2, v157
	v_xor_b32_e32 v60, 4, v157
	v_xor_b32_e32 v61, 8, v157
	v_xor_b32_e32 v62, 16, v157
	v_xor_b32_e32 v63, 32, v157
	s_mov_b64 s[48:49], -1
	s_waitcnt vmcnt(6)
	v_pk_mul_f32 v[10:11], v[2:3], v[10:11]
	s_waitcnt vmcnt(5)
	v_pk_mul_f32 v[12:13], v[4:5], v[12:13]
	v_pk_mul_f32 v[8:9], v[0:1], v[8:9]
	s_waitcnt vmcnt(4)
	v_pk_add_f32 v[30:31], v[30:31], 1.0 op_sel_hi:[1,0]
	s_waitcnt vmcnt(3)
	v_pk_add_f32 v[36:37], v[36:37], 1.0 op_sel_hi:[1,0]
	v_pk_add_f32 v[34:35], v[34:35], 1.0 op_sel_hi:[1,0]
	v_pk_mul_f32 v[14:15], v[6:7], v[14:15]
	v_pk_add_f32 v[32:33], v[32:33], 1.0 op_sel_hi:[1,0]
	v_pk_mul_f32 v[12:13], v[12:13], v[30:31]
	v_pk_mul_f32 v[30:31], v[10:11], v[36:37]
	v_pk_mul_f32 v[10:11], v[8:9], v[34:35]
	v_pk_mul_f32 v[14:15], v[14:15], v[32:33]
	v_cvt_pk_bf16_f32 v8, v12, v13
	v_cvt_pk_bf16_f32 v10, v10, v11
	v_cvt_pk_bf16_f32 v11, v30, v31
	v_mul_f32_e32 v5, v5, v5
	v_cvt_pk_bf16_f32 v9, v14, v15
	global_store_dwordx4 v[22:23], v[8:11], off
	global_load_dwordx4 v[8:11], v[28:29], off offset:2048 nt
	s_nop 0
	global_load_dwordx4 v[30:33], v[16:17], off offset:2048
	global_load_dwordx4 v[34:37], v[42:43], off offset:2048
	global_load_dwordx4 v[12:15], v[28:29], off offset:2064 nt
	global_load_dwordx4 v[38:41], v[16:17], off offset:2064
	s_nop 0
	global_load_dwordx4 v[42:45], v[42:43], off offset:2064
	v_lshl_add_u64 v[28:29], v[28:29], 0, s[30:31]
	v_mul_f32_e32 v7, v7, v7
	v_mul_f32_e32 v1, v1, v1
	v_fmac_f32_e32 v5, v4, v4
	v_fmac_f32_e32 v7, v6, v6
	v_mul_f32_e32 v3, v3, v3
	v_fmac_f32_e32 v1, v0, v0
	v_add_f32_e32 v0, v5, v7
	v_fmac_f32_e32 v3, v2, v2
	v_add_f32_e32 v0, v0, v1
	v_add_f32_e32 v0, v3, v0
	s_waitcnt vmcnt(5)
	v_mul_f32_e32 v1, v9, v9
	s_waitcnt vmcnt(4)
	v_pk_mul_f32 v[32:33], v[10:11], v[32:33]
	v_pk_mul_f32 v[30:31], v[8:9], v[30:31]
	s_waitcnt vmcnt(3)
	v_pk_add_f32 v[36:37], v[36:37], 1.0 op_sel_hi:[1,0]
	v_pk_add_f32 v[34:35], v[34:35], 1.0 op_sel_hi:[1,0]
	s_waitcnt vmcnt(1)
	v_pk_mul_f32 v[40:41], v[14:15], v[40:41]
	v_pk_mul_f32 v[38:39], v[12:13], v[38:39]
	s_waitcnt vmcnt(0)
	v_pk_add_f32 v[44:45], v[44:45], 1.0 op_sel_hi:[1,0]
	v_pk_add_f32 v[42:43], v[42:43], 1.0 op_sel_hi:[1,0]
	v_pk_mul_f32 v[32:33], v[32:33], v[36:37]
	v_pk_mul_f32 v[30:31], v[30:31], v[34:35]
	v_pk_mul_f32 v[34:35], v[40:41], v[44:45]
	v_pk_mul_f32 v[36:37], v[38:39], v[42:43]
	v_cvt_pk_bf16_f32 v30, v30, v31
	v_cvt_pk_bf16_f32 v31, v32, v33
	v_cvt_pk_bf16_f32 v33, v34, v35
	v_mul_f32_e32 v2, v11, v11
	v_cvt_pk_bf16_f32 v32, v36, v37
	global_store_dwordx4 v[22:23], v[30:33], off offset:1024
	global_load_dwordx4 v[30:33], v[54:55], off nt
	s_nop 0
	global_load_dwordx4 v[34:37], v[18:19], off
	global_load_dwordx4 v[38:41], v[26:27], off
	global_load_dwordx4 v[42:45], v[18:19], off offset:16
	s_nop 0
	global_load_dwordx4 v[46:49], v[46:47], off offset:16 nt
	v_mul_f32_e32 v3, v13, v13
	global_load_dwordx4 v[50:53], v[50:51], off offset:16
	v_fmac_f32_e32 v1, v8, v8
	v_fmac_f32_e32 v2, v10, v10
	v_mul_f32_e32 v4, v15, v15
	v_fmac_f32_e32 v3, v12, v12
	v_add_f32_e32 v1, v1, v2
	v_fmac_f32_e32 v4, v14, v14
	v_add_f32_e32 v1, v1, v3
	v_add_f32_e32 v1, v4, v1
	v_add_f32_e32 v0, v0, v1
	s_waitcnt vmcnt(3)
; __device__ __forceinline__ unsigned pk2(float lo, float hi) { unsigned r; asm("v_cvt_pk_bf16_f32 %0, %1, %2" : "=v"(r) : "v"(lo), "v"(hi)); return r; }
; __device__ __forceinline__ void p0c(LAS unsigned char* lds, int G, const int wave_s) {
;     ...
;           const int v = vec_of_row(row); const float* xr = isc ? Pp->in[2] + (size_t)(row - ML) * D : Pp->in[0] + (size_t)row * D; float s = 0.f;
; #pragma unroll
;           for (int j = 0; j < 4; ++j) { const int c = lane * 8 + 512 * j; const f32x4 a = __builtin_nontemporal_load((const f32x4*)(xr + c)), b = __builtin_nontemporal_load((const f32x4*)(xr + c + 4));
;               s += (a[0] * a[0] + a[1] * a[1]) + (a[2] * a[2] + a[3] * a[3]) + (b[0] * b[0] + b[1] * b[1]) + (b[2] * b[2] + b[3] * b[3]);
;               const f32x4 g0 = *(const f32x4*)(Pp->in[4] + c), g1 = *(const f32x4*)(Pp->in[4] + c + 4), m0 = *(const f32x4*)(MOD + (size_t)v * 6 * D + D + c), m1 = *(const f32x4*)(MOD + (size_t)v * 6 * D + D + c + 4);
;               const f32x4 ga = a * g0 * (m0 + 1.0f), gb = b * g1 * (m1 + 1.0f);
;               u32x4 w; w.x = pk2(ga[0], ga[1]); w.y = pk2(ga[2], ga[3]); w.z = pk2(gb[0], gb[1]); w.w = pk2(gb[2], gb[3]);
;               *(u32x4*)(AN + (size_t)row * D + c) = w; }
;           s = wave_sum(s);
;           if (!isc) { if (lane < 32) SSQ[((size_t)(lane >> 2) * MT + row) * 4 + (lane & 3)] = lane == 0 ? s : 0.f; }
;           else if (lane < 32) SSQC[(size_t)lane * MC + (row - ML)] = lane == 0 ? s : 0.f; } }
	v_pk_add_f32 v[40:41], v[40:41], 1.0 op_sel_hi:[1,0]
	v_pk_mul_f32 v[36:37], v[32:33], v[36:37]
	v_pk_mul_f32 v[34:35], v[30:31], v[34:35]
	v_pk_add_f32 v[38:39], v[38:39], 1.0 op_sel_hi:[1,0]
	s_waitcnt vmcnt(1)
	v_pk_mul_f32 v[44:45], v[48:49], v[44:45]
	v_pk_mul_f32 v[42:43], v[46:47], v[42:43]
	s_waitcnt vmcnt(0)
	v_pk_add_f32 v[52:53], v[52:53], 1.0 op_sel_hi:[1,0]
	v_pk_add_f32 v[50:51], v[50:51], 1.0 op_sel_hi:[1,0]
	v_pk_mul_f32 v[36:37], v[36:37], v[40:41]
	v_pk_mul_f32 v[34:35], v[34:35], v[38:39]
	v_pk_mul_f32 v[38:39], v[44:45], v[52:53]
	v_pk_mul_f32 v[40:41], v[42:43], v[50:51]
	v_cvt_pk_bf16_f32 v34, v34, v35
	v_cvt_pk_bf16_f32 v35, v36, v37
	v_cvt_pk_bf16_f32 v37, v38, v39
	v_mul_f32_e32 v1, v31, v31
	v_cvt_pk_bf16_f32 v36, v40, v41
	global_store_dwordx4 v[22:23], v[34:37], off offset:2048
	global_load_dwordx4 v[34:37], v[54:55], off offset:2048 nt
	v_mul_f32_e32 v2, v33, v33
	global_load_dwordx4 v[38:41], v[28:29], off offset:16 nt
	global_load_dwordx4 v[42:45], v[20:21], off offset:16
	global_load_dwordx4 v[50:53], v[20:21], off
	v_and_b32_e32 v54, 64, v157
	global_load_dwordx4 v[26:29], v[26:27], off offset:2048
	v_add_u32_e32 v64, 64, v54
	global_load_dwordx4 v[54:57], v[24:25], off offset:16
	v_mul_f32_e32 v3, v47, v47
	v_fmac_f32_e32 v1, v30, v30
	v_fmac_f32_e32 v2, v32, v32
	v_mul_f32_e32 v4, v49, v49
	v_fmac_f32_e32 v3, v46, v46
	v_add_f32_e32 v1, v1, v2
	v_fmac_f32_e32 v4, v48, v48
	v_add_f32_e32 v1, v1, v3
	v_add_f32_e32 v1, v4, v1
	v_add_f32_e32 v0, v0, v1
	v_cmp_lt_i32_e32 vcc, v58, v64
	s_waitcnt vmcnt(5)
	v_mul_f32_e32 v1, v35, v35
	v_mul_f32_e32 v2, v37, v37
	s_waitcnt vmcnt(4)
	v_mul_f32_e32 v3, v39, v39
	v_fmac_f32_e32 v1, v34, v34
	v_fmac_f32_e32 v2, v36, v36
	v_mul_f32_e32 v4, v41, v41
	v_fmac_f32_e32 v3, v38, v38
	v_add_f32_e32 v1, v1, v2
	v_fmac_f32_e32 v4, v40, v40
	v_add_f32_e32 v1, v1, v3
	v_cndmask_b32_e32 v24, v157, v58, vcc
	v_add_f32_e32 v1, v4, v1
	v_lshlrev_b32_e32 v24, 2, v24
	v_add_f32_e32 v0, v0, v1
	ds_bpermute_b32 v1, v24, v0
	v_cmp_lt_i32_e32 vcc, v59, v64
	s_waitcnt vmcnt(1)
	v_pk_add_f32 v[6:7], v[26:27], 1.0 op_sel_hi:[1,0]
	v_pk_mul_f32 v[8:9], v[40:41], v[44:45]
	v_cndmask_b32_e32 v25, v157, v59, vcc
	v_lshlrev_b32_e32 v3, 2, v25
	s_waitcnt lgkmcnt(0)
	v_add_f32_e32 v5, v0, v1
	ds_bpermute_b32 v3, v3, v5
	v_cmp_lt_i32_e32 vcc, v60, v64
	v_pk_mul_f32 v[0:1], v[36:37], v[52:53]
	s_waitcnt vmcnt(0)
	v_pk_add_f32 v[14:15], v[54:55], 1.0 op_sel_hi:[1,0]
	v_cndmask_b32_e32 v58, v157, v60, vcc
	v_lshlrev_b32_e32 v4, 2, v58
	s_waitcnt lgkmcnt(0)
	v_add_f32_e32 v11, v5, v3
	ds_bpermute_b32 v12, v4, v11
	v_cmp_lt_i32_e32 vcc, v61, v64
	v_pk_add_f32 v[4:5], v[28:29], 1.0 op_sel_hi:[1,0]
	s_waitcnt lgkmcnt(0)
	v_add_f32_e32 v26, v11, v12
	v_cndmask_b32_e32 v59, v157, v61, vcc
	v_lshlrev_b32_e32 v10, 2, v59
	ds_bpermute_b32 v27, v10, v26
	v_cmp_lt_i32_e32 vcc, v62, v64
	v_pk_add_f32 v[12:13], v[56:57], 1.0 op_sel_hi:[1,0]
	v_pk_mul_f32 v[4:5], v[0:1], v[4:5]
	v_cndmask_b32_e32 v60, v157, v62, vcc
	v_lshlrev_b32_e32 v24, 2, v60
	s_waitcnt lgkmcnt(0)
	v_add_f32_e32 v26, v26, v27
	ds_bpermute_b32 v24, v24, v26
	v_cmp_lt_i32_e32 vcc, v63, v64
	v_pk_mul_f32 v[10:11], v[38:39], v[42:43]
	s_nop 0
	v_cndmask_b32_e32 v2, v157, v63, vcc
	v_lshlrev_b32_e32 v25, 2, v2
	v_pk_mul_f32 v[2:3], v[34:35], v[50:51]
	s_and_b64 vcc, exec, s[10:11]
	v_pk_mul_f32 v[0:1], v[2:3], v[6:7]
	v_pk_mul_f32 v[6:7], v[8:9], v[12:13]
	s_waitcnt lgkmcnt(0)
	v_add_f32_e32 v8, v26, v24
	ds_bpermute_b32 v9, v25, v8
	v_pk_mul_f32 v[2:3], v[10:11], v[14:15]
	v_cvt_pk_bf16_f32 v0, v0, v1
	v_cvt_pk_bf16_f32 v1, v4, v5
	s_nop 0
	v_cvt_pk_bf16_f32 v2, v2, v3
	v_cvt_pk_bf16_f32 v3, v6, v7
	global_store_dwordx4 v[22:23], v[0:3], off offset:3072
	s_waitcnt lgkmcnt(0)
	s_nop 0
	v_add_f32_e32 v0, v8, v9
	s_cbranch_vccnz .LBB0_152
	s_andn2_b64 vcc, exec, s[48:49]
	s_cbranch_vccnz .LBB0_141
	s_branch .LBB0_155
